# mix phase: the workgroup with odd HW_ID threadgroup slot runs the MLA up-projection GEMMs before its hyena item, the other after (overlap of the latency-bound GEMM tiles with the other workgroup's MFM
# baseline (speedup 1.0000x reference)
; DI void phase_mix_a(const Params& p, int layer, char* smem) {
;   const bf16_t* wl = (const bf16_t*)(p.ws + OFF_W) + (size_t)layer * WL;
;   for (int it = blockIdx.x; it < 512; it += gridDim.x) {
;     const int xc = it & 7, k = it >> 3;
;     hyena_item(p, layer, (k >> 1) * 8 + xc, k & 1, smem);
;   }
.LBB0_565:
	s_or_b64 exec, exec, s[0:1]
	s_getreg_b32 s0, hwreg(HW_REG_HW_ID, 16, 4)
	s_and_b32 s0, s0, 1
	s_nop 1
	v_writelane_b32 v255, s0, 6
	s_cmp_eq_u32 s0, 1
	s_cbranch_scc1 .LBB0_599
.Lsw_back:
	v_readlane_b32 s0, v235, 46
	v_readlane_b32 s1, v235, 47
	s_mov_b64 s[34:35], s[74:75]
	s_andn2_b64 vcc, exec, s[0:1]
	s_waitcnt lgkmcnt(0)
	s_barrier
	s_cbranch_vccnz .LBB0_586
	s_mov_b32 s53, s92
	s_lshl_b32 s74, s52, 9
	s_mul_i32 s10, s52, 0x2400
	s_lshl_b64 s[6:7], s[52:53], 19
	s_or_b32 s14, s74, 0x100
	s_mul_i32 s0, s52, 0x300
	s_mov_b32 s1, s92
	s_add_u32 s75, s62, s10
	s_addc_u32 s76, s63, 0
	s_lshl_b64 s[0:1], s[0:1], 2
	s_add_u32 s77, s64, s0
	s_addc_u32 s88, s65, s1
	v_readlane_b32 s0, v235, 48
	s_add_u32 s6, s0, s6
	v_readlane_b32 s0, v235, 49
	s_addc_u32 s7, s0, s7
	v_readlane_b32 s89, v236, 4
	s_branch .LBB0_568

; DI void phase_mix_a(const Params& p, int layer, char* smem) {
;     ...
;   for (int it = blockIdx.x; it < 512; it += gridDim.x) {
;     const int xc = it & 7, k = it >> 3;
;     hyena_item(p, layer, (k >> 1) * 8 + xc, k & 1, smem);
;   }
;   if (layer == 0)
;     for (int it = blockIdx.x; it < NB * 256; it += gridDim.x) hyena_ctx_item(p, layer, it >> 8, it & 255, smem);
;   const int MT = NTOK / 128;
;   gemm_phase<EPI_QUP>(p, layer, (const bf16_t*)(p.ws + OFF_MQN), 256, wl + W_UQ, 256, 256, (layer == 0) ? MT : NLAT / 128, 5, smem);
;   gemm_phase<EPI_KVUP>(p, layer, (const bf16_t*)(p.ws + OFF_MKVN), 128, wl + W_UKV, 128, 128, MT, 6, smem, true);
.LBB0_599:
	v_readlane_b32 s80, v234, 34
	v_readlane_b32 s82, v234, 36
	v_readlane_b32 s84, v234, 38
	v_readlane_b32 s86, v234, 40
	v_readlane_b32 s88, v234, 42
	v_readlane_b32 s76, v234, 44
	v_readlane_b32 s53, v234, 29
	v_readlane_b32 s54, v234, 30
	v_readlane_b32 s34, v234, 31
	v_readlane_b32 s35, v234, 32
	v_readlane_b32 s14, v234, 33
	v_readlane_b32 s81, v234, 35
	v_readlane_b32 s83, v234, 37
	v_readlane_b32 s85, v234, 39
	v_readlane_b32 s87, v234, 41
	v_readlane_b32 s89, v234, 43
	v_readlane_b32 s77, v234, 45
	v_readlane_b32 s0, v255, 6
	s_nop 3
	s_cmp_eq_u32 s0, 2
	s_cbranch_scc1 .LBB0_1397
	s_mov_b32 s100, 4
	s_branch .Lmg_entry
.LBB0_1397:
	v_mov_b32_e32 v0, v143
	v_readlane_b32 s0, v255, 6
	s_nop 3
	s_cmp_eq_u32 s0, 1
	s_cbranch_scc0 .Lsw_cont
	s_mov_b32 s0, 2
	s_nop 1
	v_writelane_b32 v255, s0, 6
	s_branch .Lsw_back
